# SwiGLU / FFN2-in row-scale sums and EpiZ row-scale reduction block: remaining lane^16 / lane^32 ds_bpermute halves converted to permlane swaps
# baseline (speedup 1.0000x reference)
.LBB0_935:
	s_and_b64 s[78:79], s[8:9], exec
	s_cselect_b32 s7, 0, 32
	v_or_b32_e32 v130, s7, v174
	s_ashr_i32 s7, s6, 31
	s_lshl_b64 s[6:7], s[6:7], 8
	v_lshl_add_u64 v[198:199], s[6:7], 0, v[186:187]
	v_lshl_add_u64 v[146:147], s[48:49], 0, v[0:1]
	v_lshlrev_b64 v[196:197], 6, v[198:199]
	v_lshl_add_u64 v[146:147], v[146:147], 0, v[196:197]
	v_add_co_u32_e32 v150, vcc, s82, v146
	v_lshlrev_b32_e32 v194, 2, v174
	v_lshlrev_b32_e32 v134, 2, v130
	s_mov_b64 s[6:7], 0x10380000
	v_addc_co_u32_e32 v151, vcc, 0, v147, vcc
	global_load_dwordx4 v[138:141], v194, s[50:51] offset:16
	global_load_dwordx4 v[142:145], v194, s[50:51]
	global_load_dwordx4 v[130:133], v134, s[50:51] offset:16
	s_nop 0
	global_load_dwordx4 v[134:137], v134, s[50:51]
	v_lshl_add_u64 v[148:149], v[146:147], 0, s[6:7]
	global_load_dwordx4 v[202:205], v[150:151], off
	global_load_dwordx4 v[206:209], v[148:149], off offset:1024
	global_load_dwordx4 v[212:215], v[148:149], off offset:2048
	global_load_dwordx4 v[162:165], v[148:149], off offset:3072
	v_add_co_u32_e32 v146, vcc, s55, v146
	s_or_b64 s[42:43], s[42:43], s[40:41]
	s_nop 0
	v_addc_co_u32_e32 v147, vcc, 0, v147, vcc
	global_load_dwordx4 v[158:161], v[146:147], off
	global_load_dwordx4 v[154:157], v[146:147], off offset:1024
	global_load_dwordx4 v[150:153], v[146:147], off offset:2048
	s_nop 0
	global_load_dwordx4 v[146:149], v[146:147], off offset:3072
	s_andn2_b64 vcc, exec, s[42:43]
	s_waitcnt vmcnt(0)
	v_mov_b32_e32 v176, v203
	v_mov_b32_e32 v177, v204
	v_mov_b32_e32 v203, v205
	v_pk_add_f32 v[176:177], v[176:177], v[202:203]
	v_add_f32_e32 v162, v162, v163
	v_add_f32_e32 v176, v176, v177
	v_add_f32_e32 v163, v164, v165
	v_mov_b32_e32 v177, v176
	s_nop 1
	v_permlane16_swap_b32_e32 v177, v176
	v_add_f32_e32 v162, v162, v163
	v_add_f32_e32 v158, v158, v159
	v_add_f32_e32 v159, v160, v161
	s_waitcnt lgkmcnt(0)
	v_add_f32_e32 v176, v176, v177
	v_add_f32_e32 v158, v158, v159
	v_mov_b32_e32 v177, v176
	s_nop 1
	v_permlane32_swap_b32_e32 v177, v176
	v_add_f32_e32 v154, v154, v155
	v_add_f32_e32 v155, v156, v157
	v_add_f32_e32 v154, v154, v155
	s_waitcnt lgkmcnt(0)
	v_add_f32_e32 v176, v176, v177
	v_fmamk_f32 v176, v176, 0x3a800000, v228
	v_rsq_f32_e32 v200, v176
	v_add_f32_e32 v176, v206, v207
	v_add_f32_e32 v177, v208, v209
	v_add_f32_e32 v176, v176, v177
	v_mov_b32_e32 v177, v176
	v_mov_b32_e32 v252, v176
	s_nop 1
	v_permlane16_swap_b32_e32 v177, v252
	v_add_f32_e32 v150, v150, v151
	v_add_f32_e32 v151, v152, v153
	v_add_f32_e32 v150, v150, v151
	s_waitcnt lgkmcnt(0)
	v_add_f32_e32 v193, v177, v252
	v_mov_b32_e32 v176, v1
	v_add_f32_e32 v177, v214, v215
	v_mbcnt_lo_u32_b32 v176, -1, v176
	v_mbcnt_hi_u32_b32 v176, -1, v176
	v_lshlrev_b32_e32 v176, 2, v176
	v_xor_b32_e32 v176, 0x80, v176
	ds_bpermute_b32 v210, v176, v193
	v_add_f32_e32 v176, v212, v213
	v_add_f32_e32 v176, v176, v177
	v_add_f32_e32 v146, v146, v147
	v_mov_b32_e32 v177, v176
	v_mov_b32_e32 v252, v176
	s_nop 1
	v_permlane16_swap_b32_e32 v177, v252
	v_add_f32_e32 v147, v148, v149
	v_add_f32_e32 v146, v146, v147
	v_pk_mul_f32 v[152:153], v[114:115], v[200:201] op_sel_hi:[1,0]
	s_waitcnt lgkmcnt(0)
	v_add_f32_e32 v208, v177, v252
	v_mov_b32_e32 v176, v1
	v_cndmask_b32_e64 v114, 0, 1, s[42:43]
	v_mov_b32_e32 v163, v162
	v_mov_b32_e32 v252, v162
	s_nop 1
	v_permlane16_swap_b32_e32 v163, v252
	v_mbcnt_lo_u32_b32 v176, -1, v176
	v_mbcnt_hi_u32_b32 v176, -1, v176
	v_lshlrev_b32_e32 v176, 2, v176
	v_xor_b32_e32 v176, 0x80, v176
	s_waitcnt lgkmcnt(0)
	v_add_f32_e32 v206, v163, v252
	v_mov_b32_e32 v162, v1
	ds_bpermute_b32 v209, v176, v208
	v_mov_b32_e32 v159, v158
	v_mov_b32_e32 v252, v158
	s_nop 1
	v_permlane16_swap_b32_e32 v159, v252
	v_mbcnt_lo_u32_b32 v162, -1, v162
	v_mbcnt_hi_u32_b32 v162, -1, v162
	v_lshlrev_b32_e32 v162, 2, v162
	v_xor_b32_e32 v162, 0x80, v162
	s_waitcnt lgkmcnt(0)
	v_add_f32_e32 v204, v159, v252
	v_mov_b32_e32 v158, v1
	ds_bpermute_b32 v207, v162, v206
	v_mov_b32_e32 v155, v154
	v_mov_b32_e32 v252, v154
	s_nop 1
	v_permlane16_swap_b32_e32 v155, v252
	v_mbcnt_lo_u32_b32 v158, -1, v158
	v_mbcnt_hi_u32_b32 v158, -1, v158
	v_lshlrev_b32_e32 v158, 2, v158
	v_xor_b32_e32 v158, 0x80, v158
	s_waitcnt lgkmcnt(0)
	v_add_f32_e32 v202, v155, v252
	v_mov_b32_e32 v154, v1
	ds_bpermute_b32 v205, v158, v204
	v_mov_b32_e32 v151, v150
	v_mov_b32_e32 v252, v150
	s_nop 1
	v_permlane16_swap_b32_e32 v151, v252
	v_mbcnt_lo_u32_b32 v154, -1, v154
	v_mbcnt_hi_u32_b32 v154, -1, v154
	v_lshlrev_b32_e32 v154, 2, v154
	v_xor_b32_e32 v154, 0x80, v154
	s_waitcnt lgkmcnt(0)
	v_add_f32_e32 v164, v151, v252
	v_mov_b32_e32 v150, v1
	ds_bpermute_b32 v203, v154, v202
	v_mov_b32_e32 v147, v146
	v_mov_b32_e32 v252, v146
	s_nop 1
	v_permlane16_swap_b32_e32 v147, v252
	v_mbcnt_lo_u32_b32 v150, -1, v150
	v_mbcnt_hi_u32_b32 v150, -1, v150
	v_lshlrev_b32_e32 v150, 2, v150
	v_xor_b32_e32 v150, 0x80, v150
	s_waitcnt lgkmcnt(0)
	v_add_f32_e32 v162, v147, v252
	v_mov_b32_e32 v146, v1
	ds_bpermute_b32 v165, v150, v164
	v_mbcnt_lo_u32_b32 v146, -1, v146
	v_mbcnt_hi_u32_b32 v146, -1, v146
	v_lshlrev_b32_e32 v146, 2, v146
	v_xor_b32_e32 v146, 0x80, v146
	ds_bpermute_b32 v163, v146, v162
	v_pk_mul_f32 v[148:149], v[126:127], v[200:201] op_sel_hi:[1,0]
	v_pk_mul_f32 v[158:159], v[128:129], v[200:201] op_sel_hi:[1,0]
	v_pk_mul_f32 v[156:157], v[122:123], v[200:201] op_sel_hi:[1,0]
	v_pk_mul_f32 v[160:161], v[124:125], v[200:201] op_sel_hi:[1,0]
	v_pk_mul_f32 v[146:147], v[118:119], v[200:201] op_sel_hi:[1,0]
	v_pk_mul_f32 v[154:155], v[120:121], v[200:201] op_sel_hi:[1,0]
	v_pk_mul_f32 v[150:151], v[116:117], v[200:201] op_sel_hi:[1,0]
	v_cmp_ne_u32_e64 s[6:7], 1, v114
	s_cbranch_vccnz .LBB0_937
	v_mul_f32_e32 v114, 0x3d372713, v148
	v_mul_f32_e32 v115, 0x3d372713, v149
	v_mul_f32_e32 v114, v148, v114
	v_mul_f32_e32 v115, v149, v115
	v_fma_f32 v114, v148, v114, v148
	v_fma_f32 v115, v149, v115, v149
	v_mul_f32_e32 v114, 0x3f4c422a, v114
	v_mul_f32_e32 v115, 0x3f4c422a, v115
	v_mul_f32_e32 v114, 0xc038aa3b, v114
	v_mul_f32_e32 v115, 0xc038aa3b, v115
	v_exp_f32_e32 v114, v114
	v_exp_f32_e32 v115, v115
	v_add_f32_e32 v114, 1.0, v114
	v_add_f32_e32 v115, 1.0, v115
	v_rcp_f32_e32 v114, v114
	v_rcp_f32_e32 v115, v115
	s_nop 0
	v_pk_mul_f32 v[148:149], v[148:149], v[114:115]
	v_mul_f32_e32 v114, 0x3d372713, v158
	v_mul_f32_e32 v115, 0x3d372713, v159
	v_mul_f32_e32 v114, v158, v114
	v_mul_f32_e32 v115, v159, v115
	v_fma_f32 v114, v158, v114, v158
	v_fma_f32 v115, v159, v115, v159
	v_mul_f32_e32 v114, 0x3f4c422a, v114
	v_mul_f32_e32 v115, 0x3f4c422a, v115
	v_mul_f32_e32 v114, 0xc038aa3b, v114
	v_mul_f32_e32 v115, 0xc038aa3b, v115
	v_exp_f32_e32 v114, v114
	v_exp_f32_e32 v115, v115
	v_add_f32_e32 v114, 1.0, v114
	v_add_f32_e32 v115, 1.0, v115
	v_rcp_f32_e32 v114, v114
	v_rcp_f32_e32 v115, v115
	s_nop 0
	v_pk_mul_f32 v[158:159], v[158:159], v[114:115]
	v_mul_f32_e32 v114, 0x3d372713, v156
	v_mul_f32_e32 v115, 0x3d372713, v157
	v_mul_f32_e32 v114, v156, v114
	v_mul_f32_e32 v115, v157, v115
	v_fma_f32 v114, v156, v114, v156
	v_fma_f32 v115, v157, v115, v157
	v_mul_f32_e32 v114, 0x3f4c422a, v114
	v_mul_f32_e32 v115, 0x3f4c422a, v115
	v_mul_f32_e32 v114, 0xc038aa3b, v114
	v_mul_f32_e32 v115, 0xc038aa3b, v115
	v_exp_f32_e32 v114, v114
	v_exp_f32_e32 v115, v115
	v_add_f32_e32 v114, 1.0, v114
	v_add_f32_e32 v115, 1.0, v115
	v_rcp_f32_e32 v114, v114
	v_rcp_f32_e32 v115, v115
	s_nop 0
	v_pk_mul_f32 v[156:157], v[156:157], v[114:115]
	v_mul_f32_e32 v114, 0x3d372713, v160
	v_mul_f32_e32 v115, 0x3d372713, v161
	v_mul_f32_e32 v114, v160, v114
	v_mul_f32_e32 v115, v161, v115
	v_fma_f32 v114, v160, v114, v160
	v_fma_f32 v115, v161, v115, v161
	v_mul_f32_e32 v114, 0x3f4c422a, v114
	v_mul_f32_e32 v115, 0x3f4c422a, v115
	v_mul_f32_e32 v114, 0xc038aa3b, v114
	v_mul_f32_e32 v115, 0xc038aa3b, v115
	v_exp_f32_e32 v114, v114
	v_exp_f32_e32 v115, v115
	v_add_f32_e32 v114, 1.0, v114
	v_add_f32_e32 v115, 1.0, v115
	v_rcp_f32_e32 v114, v114
	v_rcp_f32_e32 v115, v115
	s_nop 0
	v_pk_mul_f32 v[160:161], v[160:161], v[114:115]
	v_mul_f32_e32 v114, 0x3d372713, v146
	v_mul_f32_e32 v115, 0x3d372713, v147
	v_mul_f32_e32 v114, v146, v114
	v_mul_f32_e32 v115, v147, v115
	v_fma_f32 v114, v146, v114, v146
	v_fma_f32 v115, v147, v115, v147
	v_mul_f32_e32 v114, 0x3f4c422a, v114
	v_mul_f32_e32 v115, 0x3f4c422a, v115
	v_mul_f32_e32 v114, 0xc038aa3b, v114
	v_mul_f32_e32 v115, 0xc038aa3b, v115
	v_exp_f32_e32 v114, v114
	v_exp_f32_e32 v115, v115
	v_add_f32_e32 v114, 1.0, v114
	v_add_f32_e32 v115, 1.0, v115
	v_rcp_f32_e32 v114, v114
	v_rcp_f32_e32 v115, v115
	s_nop 0
	v_pk_mul_f32 v[146:147], v[146:147], v[114:115]
	v_mul_f32_e32 v114, 0x3d372713, v154
	v_mul_f32_e32 v115, 0x3d372713, v155
	v_mul_f32_e32 v114, v154, v114
	v_mul_f32_e32 v115, v155, v115
	v_fma_f32 v114, v154, v114, v154
	v_fma_f32 v115, v155, v115, v155
	v_mul_f32_e32 v114, 0x3f4c422a, v114
	v_mul_f32_e32 v115, 0x3f4c422a, v115
	v_mul_f32_e32 v114, 0xc038aa3b, v114
	v_mul_f32_e32 v115, 0xc038aa3b, v115
	v_exp_f32_e32 v114, v114
	v_exp_f32_e32 v115, v115
	v_add_f32_e32 v114, 1.0, v114
	v_add_f32_e32 v115, 1.0, v115
	v_rcp_f32_e32 v114, v114
	v_rcp_f32_e32 v115, v115
	s_nop 0
	v_pk_mul_f32 v[154:155], v[154:155], v[114:115]
	v_mul_f32_e32 v114, 0x3d372713, v152
	v_mul_f32_e32 v115, 0x3d372713, v153
	v_mul_f32_e32 v114, v152, v114
	v_mul_f32_e32 v115, v153, v115
	v_fma_f32 v114, v152, v114, v152
	v_fma_f32 v115, v153, v115, v153
	v_mul_f32_e32 v114, 0x3f4c422a, v114
	v_mul_f32_e32 v115, 0x3f4c422a, v115
	v_mul_f32_e32 v114, 0xc038aa3b, v114
	v_mul_f32_e32 v115, 0xc038aa3b, v115
	v_exp_f32_e32 v114, v114
	v_exp_f32_e32 v115, v115
	v_add_f32_e32 v114, 1.0, v114
	v_add_f32_e32 v115, 1.0, v115
	v_rcp_f32_e32 v114, v114
	v_rcp_f32_e32 v115, v115
	s_nop 0
	v_pk_mul_f32 v[152:153], v[152:153], v[114:115]
	v_mul_f32_e32 v114, 0x3d372713, v150
	v_mul_f32_e32 v115, 0x3d372713, v151
	v_mul_f32_e32 v114, v150, v114
	v_mul_f32_e32 v115, v151, v115
	v_fma_f32 v114, v150, v114, v150
	v_fma_f32 v115, v151, v115, v151
	v_mul_f32_e32 v114, 0x3f4c422a, v114
	v_mul_f32_e32 v115, 0x3f4c422a, v115
	v_mul_f32_e32 v114, 0xc038aa3b, v114
	v_mul_f32_e32 v115, 0xc038aa3b, v115
	v_exp_f32_e32 v114, v114
	v_exp_f32_e32 v115, v115
	v_add_f32_e32 v114, 1.0, v114
	v_add_f32_e32 v115, 1.0, v115
	v_rcp_f32_e32 v114, v114
	v_rcp_f32_e32 v115, v115
	s_nop 0
	v_pk_mul_f32 v[150:151], v[150:151], v[114:115]
.LBB0_937:
	v_pk_mul_f32 v[114:115], s[44:45], v[142:143] op_sel_hi:[0,1]
	v_cndmask_b32_e64 v121, v115, 1.0, s[46:47]
	v_cndmask_b32_e64 v120, v114, 1.0, s[46:47]
	v_pk_mul_f32 v[114:115], s[44:45], v[138:139] op_sel_hi:[0,1]
	v_cndmask_b32_e64 v119, v115, 1.0, s[46:47]
	v_cndmask_b32_e64 v118, v114, 1.0, s[46:47]
	v_pk_mul_f32 v[114:115], s[44:45], v[134:135] op_sel_hi:[0,1]
	v_cndmask_b32_e64 v125, v115, 1.0, s[46:47]
	v_cndmask_b32_e64 v124, v114, 1.0, s[46:47]
	v_pk_mul_f32 v[114:115], s[44:45], v[130:131] op_sel_hi:[0,1]
	v_cndmask_b32_e64 v123, v115, 1.0, s[46:47]
	v_cndmask_b32_e64 v122, v114, 1.0, s[46:47]
	v_pk_mul_f32 v[114:115], s[44:45], v[144:145] op_sel_hi:[0,1]
	v_cndmask_b32_e64 v129, v115, 1.0, s[46:47]
	v_cndmask_b32_e64 v128, v114, 1.0, s[46:47]
	v_pk_mul_f32 v[114:115], s[44:45], v[140:141] op_sel_hi:[0,1]
	s_xor_b64 s[42:43], s[8:9], -1
	v_cndmask_b32_e64 v127, v115, 1.0, s[46:47]
	v_cndmask_b32_e64 v126, v114, 1.0, s[46:47]
	v_pk_mul_f32 v[114:115], s[44:45], v[136:137] op_sel_hi:[0,1]
	s_or_b64 s[8:9], s[8:9], s[36:37]
	v_cndmask_b32_e64 v135, v115, 1.0, s[46:47]
	v_cndmask_b32_e64 v134, v114, 1.0, s[46:47]
	v_pk_mul_f32 v[114:115], s[44:45], v[132:133] op_sel_hi:[0,1]
	s_or_b64 s[36:37], s[40:41], s[8:9]
	v_cndmask_b32_e64 v130, v114, 1.0, s[46:47]
	v_cndmask_b32_e64 v114, 0, 1, s[36:37]
	v_cndmask_b32_e64 v131, v115, 1.0, s[46:47]
	v_cmp_ne_u32_e64 s[8:9], 1, v114
	s_andn2_b64 vcc, exec, s[36:37]
	s_cbranch_vccnz .LBB0_943
	v_pk_mul_f32 v[114:115], v[148:149], v[148:149]
	v_pk_mul_f32 v[116:117], v[158:159], v[158:159]
	v_add_f32_e32 v114, v115, v114
	v_add_f32_e32 v114, v116, v114
	v_pk_mul_f32 v[132:133], v[156:157], v[156:157]
	v_add_f32_e32 v114, v117, v114
	v_add_f32_e32 v114, v132, v114
	v_pk_mul_f32 v[136:137], v[160:161], v[160:161]
	v_add_f32_e32 v114, v133, v114
	v_add_f32_e32 v114, v136, v114
	v_add_f32_e32 v114, v137, v114
	v_mov_b32_e32 v115, v114
	s_nop 1
	v_permlane16_swap_b32_e32 v115, v114
	v_pk_mul_f32 v[116:117], v[146:147], v[146:147]
	v_pk_mul_f32 v[132:133], v[154:155], v[154:155]
	v_pk_mul_f32 v[136:137], v[152:153], v[152:153]
	v_pk_mul_f32 v[138:139], v[150:151], v[150:151]
	s_waitcnt lgkmcnt(0)
	v_add_f32_e32 v114, v114, v115
	s_mov_b64 s[36:37], -1
	v_mov_b32_e32 v115, v114
	v_mov_b32_e32 v252, v114
	s_nop 1
	v_permlane32_swap_b32_e32 v115, v252
	s_and_b64 vcc, exec, s[42:43]
	s_waitcnt lgkmcnt(0)
	v_add_f32_e32 v115, v115, v252
	v_add_f32_e32 v114, v117, v116
	v_add_f32_e32 v114, v132, v114
	v_add_f32_e32 v114, v133, v114
	v_add_f32_e32 v114, v136, v114
	v_add_f32_e32 v114, v137, v114
	v_add_f32_e32 v114, v138, v114
	v_add_f32_e32 v114, v139, v114
	v_mov_b32_e32 v116, v114
	s_nop 1
	v_permlane16_swap_b32_e32 v116, v114
	s_waitcnt lgkmcnt(0)
	v_add_f32_e32 v114, v114, v116
	s_nop 0
	v_mov_b32_e32 v116, v114
	v_mov_b32_e32 v252, v114
	s_nop 1
	v_permlane32_swap_b32_e32 v116, v252
	s_waitcnt lgkmcnt(0)
	v_add_f32_e32 v117, v116, v252
	s_cbranch_vccz .LBB0_940
	v_add_f32_e32 v114, v115, v117
	v_fmamk_f32 v114, v114, 0x3c800000, v228
	v_rsq_f32_e32 v114, v114
	s_mov_b64 s[36:37], 0

.LBB0_2492:
	s_lshl_b32 s22, s47, 2
	s_ashr_i32 s23, s22, 31
	s_lshl_b64 s[22:23], s[22:23], 2
	s_add_u32 s22, s24, s22
	s_addc_u32 s23, s25, s23
	s_add_u32 s22, s22, s44
	s_addc_u32 s23, s23, 0
	s_add_u32 s22, s22, 0x10380000
	s_addc_u32 s23, s23, 0
	s_and_b64 vcc, exec, s[6:7]
	s_cbranch_vccnz .LBB0_2496
	v_mov_b32_e32 v114, v118
	v_mov_b32_e32 v252, v118
	s_nop 1
	v_permlane16_swap_b32_e32 v114, v252
	s_waitcnt lgkmcnt(0)
	v_add_f32_e32 v114, v114, v252
	v_mov_b32_e32 v115, v114
	s_nop 1
	v_permlane32_swap_b32_e32 v115, v114
	s_and_saveexec_b64 s[24:25], s[2:3]
	s_cbranch_execz .LBB0_2495
	v_lshlrev_b64 v[116:117], 6, v[140:141]
	v_lshl_add_u64 v[116:117], s[22:23], 0, v[116:117]
	s_waitcnt lgkmcnt(0)
	v_add_f32_e32 v114, v114, v115
	global_store_dword v[116:117], v114, off

.LBB0_2513:
	v_mov_b32_e32 v98, v102
	v_mov_b32_e32 v252, v102
	s_nop 1
	v_permlane16_swap_b32_e32 v98, v252
	s_waitcnt lgkmcnt(0)
	v_add_f32_e32 v98, v98, v252
	v_mov_b32_e32 v99, v98
	s_nop 1
	v_permlane32_swap_b32_e32 v99, v98
	s_and_saveexec_b64 s[24:25], s[2:3]
	s_cbranch_execz .LBB0_2515
	v_lshlrev_b64 v[100:101], 6, v[122:123]
	v_lshl_add_u64 v[100:101], s[22:23], 0, v[100:101]
	s_waitcnt lgkmcnt(0)
	v_add_f32_e32 v98, v98, v99
	global_store_dword v[100:101], v98, off

.LBB0_2533:
	v_mov_b32_e32 v82, v86
	v_mov_b32_e32 v252, v86
	s_nop 1
	v_permlane16_swap_b32_e32 v82, v252
	s_waitcnt lgkmcnt(0)
	v_add_f32_e32 v82, v82, v252
	v_mov_b32_e32 v83, v82
	s_nop 1
	v_permlane32_swap_b32_e32 v83, v82
	s_and_saveexec_b64 s[24:25], s[2:3]
	s_cbranch_execz .LBB0_2535
	v_lshlrev_b64 v[84:85], 6, v[106:107]
	v_lshl_add_u64 v[84:85], s[22:23], 0, v[84:85]
	s_waitcnt lgkmcnt(0)
	v_add_f32_e32 v82, v82, v83
	global_store_dword v[84:85], v82, off

.LBB0_2553:
	v_mov_b32_e32 v66, v70
	v_mov_b32_e32 v252, v70
	s_nop 1
	v_permlane16_swap_b32_e32 v66, v252
	s_waitcnt lgkmcnt(0)
	v_add_f32_e32 v66, v66, v252
	v_mov_b32_e32 v67, v66
	s_nop 1
	v_permlane32_swap_b32_e32 v67, v66
	s_and_saveexec_b64 s[24:25], s[2:3]
	s_cbranch_execz .LBB0_2555
	v_lshlrev_b64 v[68:69], 6, v[90:91]
	v_lshl_add_u64 v[68:69], s[22:23], 0, v[68:69]
	s_waitcnt lgkmcnt(0)
	v_add_f32_e32 v66, v66, v67
	global_store_dword v[68:69], v66, off

.LBB0_2573:
	v_mov_b32_e32 v50, v54
	v_mov_b32_e32 v252, v54
	s_nop 1
	v_permlane16_swap_b32_e32 v50, v252
	s_waitcnt lgkmcnt(0)
	v_add_f32_e32 v50, v50, v252
	v_mov_b32_e32 v51, v50
	s_nop 1
	v_permlane32_swap_b32_e32 v51, v50
	s_and_saveexec_b64 s[24:25], s[2:3]
	s_cbranch_execz .LBB0_2575
	v_lshlrev_b64 v[52:53], 6, v[76:77]
	v_lshl_add_u64 v[52:53], s[22:23], 0, v[52:53]
	s_waitcnt lgkmcnt(0)
	v_add_f32_e32 v50, v50, v51
	global_store_dword v[52:53], v50, off

.LBB0_2593:
	v_mov_b32_e32 v34, v38
	v_mov_b32_e32 v252, v38
	s_nop 1
	v_permlane16_swap_b32_e32 v34, v252
	s_waitcnt lgkmcnt(0)
	v_add_f32_e32 v34, v34, v252
	v_mov_b32_e32 v35, v34
	s_nop 1
	v_permlane32_swap_b32_e32 v35, v34
	s_and_saveexec_b64 s[24:25], s[2:3]
	s_cbranch_execz .LBB0_2595
	v_lshlrev_b64 v[36:37], 6, v[58:59]
	v_lshl_add_u64 v[36:37], s[22:23], 0, v[36:37]
	s_waitcnt lgkmcnt(0)
	v_add_f32_e32 v34, v34, v35
	global_store_dword v[36:37], v34, off

.LBB0_2613:
	v_mov_b32_e32 v18, v22
	v_mov_b32_e32 v252, v22
	s_nop 1
	v_permlane16_swap_b32_e32 v18, v252
	s_waitcnt lgkmcnt(0)
	v_add_f32_e32 v18, v18, v252
	v_mov_b32_e32 v19, v18
	s_nop 1
	v_permlane32_swap_b32_e32 v19, v18
	s_and_saveexec_b64 s[24:25], s[2:3]
	s_cbranch_execz .LBB0_2615
	v_lshlrev_b64 v[20:21], 6, v[42:43]
	v_lshl_add_u64 v[20:21], s[22:23], 0, v[20:21]
	s_waitcnt lgkmcnt(0)
	v_add_f32_e32 v18, v18, v19
	global_store_dword v[20:21], v18, off

.LBB0_2631:
	v_mov_b32_e32 v2, v6
	v_mov_b32_e32 v252, v6
	s_nop 1
	v_permlane16_swap_b32_e32 v2, v252
	s_waitcnt lgkmcnt(0)
	v_add_f32_e32 v2, v2, v252
	v_mov_b32_e32 v3, v2
	s_nop 1
	v_permlane32_swap_b32_e32 v3, v2
	s_and_saveexec_b64 s[6:7], s[2:3]
	s_cbranch_execz .LBB0_2633
	v_lshlrev_b64 v[4:5], 6, v[18:19]
	v_lshl_add_u64 v[4:5], s[22:23], 0, v[4:5]
	s_waitcnt lgkmcnt(0)
	v_add_f32_e32 v2, v2, v3
	global_store_dword v[4:5], v2, off
